# v114 + one static s_setprio 1 for the RWKV scanner waves (reset to 0 at scanner exit)
# baseline (speedup 1.0000x reference)
.Lscan_entry:
	s_setprio 1
	s_waitcnt vmcnt(0) lgkmcnt(0)
	v_and_b32_e32 v16, 7, v161
	v_lshrrev_b32_e32 v17, 3, v161
	v_lshlrev_b32_e32 v137, 5, v16
	v_lshlrev_b32_e32 v139, 3, v17
	v_lshrrev_b32_e32 v18, 1, v16
	v_and_b32_e32 v19, 1, v16
	v_lshlrev_b32_e32 v18, 8, v18
	v_lshlrev_b32_e32 v19, 2, v19
	v_add3_u32 v84, v139, v18, v19
	v_add_u32_e32 v84, 0x7000, v84
	v_add_u32_e32 v139, 0x5000, v139
	v_mov_b32_e32 v128, 0x8008
	v_mov_b32_e32 v129, 0x8000
	v_cndmask_b32_e64 v156, v128, v129, s[42:43]
	v_and_b32_e32 v128, 15, v161
	v_lshrrev_b32_e32 v129, 4, v161
	v_lshlrev_b32_e32 v128, 4, v128
	v_mul_u32_u24_e32 v129, 0x8200, v129
	v_add_u32_e32 v128, v128, v129
	v_add_u32_e32 v128, 0x8008, v128
	v_mov_b32_e32 v16, 0
	v_mov_b32_e32 v17, 0
	v_cmp_gt_u32_e32 vcc, 32, v161
	s_and_saveexec_b64 s[0:1], vcc
	ds_write_b64 v128, v[16:17]
	s_mov_b64 exec, s[0:1]
	v_mov_b32_e32 v0, 0
	v_mov_b32_e32 v1, 0
	v_mov_b32_e32 v2, 0
	v_mov_b32_e32 v3, 0
	v_mov_b32_e32 v4, 0
	v_mov_b32_e32 v5, 0
	v_mov_b32_e32 v6, 0
	v_mov_b32_e32 v7, 0
	v_mov_b32_e32 v8, 0
	v_mov_b32_e32 v9, 0
	v_mov_b32_e32 v10, 0
	v_mov_b32_e32 v11, 0
	v_mov_b32_e32 v12, 0
	v_mov_b32_e32 v13, 0
	v_mov_b32_e32 v14, 0
	v_mov_b32_e32 v15, 0
	s_mov_b32 s1, 0
	s_movk_i32 s2, 0x80
	s_waitcnt lgkmcnt(0)
	s_barrier

.Lscan_q4:
	s_waitcnt lgkmcnt(0)
	v_pk_mul_f32 v[16:17], v[2:3], v[34:35]
	v_pk_mul_f32 v[18:19], v[10:11], v[34:35]
	ds_read_b128 v[76:79], v130 offset:256
	v_pk_fma_f32 v[16:17], v[0:1], v[32:33], v[16:17]
	v_pk_fma_f32 v[18:19], v[8:9], v[32:33], v[18:19]
	ds_read_b128 v[80:83], v130 offset:272
	v_pk_fma_f32 v[16:17], v[4:5], v[36:37], v[16:17]
	v_pk_fma_f32 v[18:19], v[12:13], v[36:37], v[18:19]
	ds_read_b128 v[90:93], v130 offset:4352
	v_pk_fma_f32 v[16:17], v[6:7], v[38:39], v[16:17]
	v_pk_fma_f32 v[18:19], v[14:15], v[38:39], v[18:19]
	ds_read_b128 v[94:97], v130 offset:4368
	v_pk_mul_f32 v[20:21], v[2:3], v[42:43]
	v_add_f32_e32 v24, v16, v17
	ds_read_b128 v[112:115], v130 offset:12544
	v_add_f32_e32 v25, v18, v19
	v_pk_mul_f32 v[22:23], v[10:11], v[42:43]
	ds_read_b128 v[116:119], v130 offset:12560
	v_add_f32_dpp v24, v24, v24 quad_perm:[1,0,3,2] row_mask:0xf bank_mask:0xf bound_ctrl:1
	v_add_f32_dpp v25, v25, v25 quad_perm:[1,0,3,2] row_mask:0xf bank_mask:0xf bound_ctrl:1
	ds_read_b128 v[120:123], v130 offset:16640
	v_pk_fma_f32 v[20:21], v[0:1], v[40:41], v[20:21]
	v_add_f32_dpp v24, v24, v24 quad_perm:[2,3,0,1] row_mask:0xf bank_mask:0xf bound_ctrl:1
	ds_read_b128 v[124:127], v130 offset:16656
	v_add_f32_dpp v25, v25, v25 quad_perm:[2,3,0,1] row_mask:0xf bank_mask:0xf bound_ctrl:1
	v_pk_fma_f32 v[22:23], v[8:9], v[40:41], v[22:23]
	ds_read_b128 v[98:101], v130 offset:8448
	v_add_f32_dpp v24, v24, v24 row_half_mirror row_mask:0xf bank_mask:0xf bound_ctrl:1
	v_add_f32_dpp v25, v25, v25 row_half_mirror row_mask:0xf bank_mask:0xf bound_ctrl:1
	ds_read_b128 v[102:105], v130 offset:8464
	v_pk_fma_f32 v[20:21], v[4:5], v[44:45], v[20:21]
	v_pk_fma_f32 v[22:23], v[12:13], v[44:45], v[22:23]
	ds_read2_b64 v[106:109], v131 offset0:64 offset1:96
	v_pk_fma_f32 v[20:21], v[6:7], v[46:47], v[20:21]
	v_pk_fma_f32 v[22:23], v[14:15], v[46:47], v[22:23]
	ds_read2_b64 v[144:147], v85 offset0:4 offset1:6
	v_add_f32_e32 v26, v20, v21
	v_add_f32_e32 v27, v22, v23
	v_pk_fma_f32 v[176:177], v[24:25], v[140:141], v[26:27] op_sel_hi:[1,0,1]
	v_pk_mul_f32 v[164:165], v[56:57], v[24:25] op_sel_hi:[1,0]
	v_pk_mul_f32 v[166:167], v[56:57], v[24:25] op_sel:[0,1]
	v_pk_mul_f32 v[168:169], v[58:59], v[24:25] op_sel_hi:[1,0]
	v_pk_mul_f32 v[170:171], v[58:59], v[24:25] op_sel:[0,1]
	v_pk_fma_f32 v[164:165], v[64:65], v[72:73], v[164:165] op_sel_hi:[1,0,1]
	v_pk_fma_f32 v[166:167], v[64:65], v[72:73], v[166:167] op_sel:[0,1,0]
	v_pk_fma_f32 v[168:169], v[66:67], v[72:73], v[168:169] op_sel_hi:[1,0,1]
	v_pk_fma_f32 v[170:171], v[66:67], v[72:73], v[170:171] op_sel:[0,1,0]
	v_pk_fma_f32 v[0:1], v[0:1], v[48:49], v[164:165]
	v_pk_fma_f32 v[8:9], v[8:9], v[48:49], v[166:167]
	v_pk_fma_f32 v[2:3], v[2:3], v[50:51], v[168:169]
	v_pk_fma_f32 v[10:11], v[10:11], v[50:51], v[170:171]
	v_pk_mul_f32 v[164:165], v[60:61], v[24:25] op_sel_hi:[1,0]
	v_pk_mul_f32 v[166:167], v[60:61], v[24:25] op_sel:[0,1]
	v_pk_mul_f32 v[168:169], v[62:63], v[24:25] op_sel_hi:[1,0]
	v_pk_mul_f32 v[170:171], v[62:63], v[24:25] op_sel:[0,1]
	v_pk_fma_f32 v[164:165], v[68:69], v[72:73], v[164:165] op_sel_hi:[1,0,1]
	v_pk_fma_f32 v[166:167], v[68:69], v[72:73], v[166:167] op_sel:[0,1,0]
	v_pk_fma_f32 v[168:169], v[70:71], v[72:73], v[168:169] op_sel_hi:[1,0,1]
	v_pk_fma_f32 v[170:171], v[70:71], v[72:73], v[170:171] op_sel:[0,1,0]
	v_pk_fma_f32 v[4:5], v[4:5], v[52:53], v[164:165]
	v_pk_fma_f32 v[12:13], v[12:13], v[52:53], v[166:167]
	v_pk_fma_f32 v[6:7], v[6:7], v[54:55], v[168:169]
	v_pk_fma_f32 v[14:15], v[14:15], v[54:55], v[170:171]
	v_pk_fma_f32 v[176:177], v[72:73], v[140:141], v[176:177] op_sel:[0,1,0]
	s_waitcnt lgkmcnt(0)
	v_pk_mul_f32 v[16:17], v[2:3], v[78:79]
	v_pk_mul_f32 v[18:19], v[10:11], v[78:79]
	ds_read_b128 v[32:35], v130 offset:512
	v_pk_fma_f32 v[16:17], v[0:1], v[76:77], v[16:17]
	v_pk_fma_f32 v[18:19], v[8:9], v[76:77], v[18:19]
	ds_read_b128 v[36:39], v130 offset:528
	v_pk_fma_f32 v[16:17], v[4:5], v[80:81], v[16:17]
	v_pk_fma_f32 v[18:19], v[12:13], v[80:81], v[18:19]
	ds_read_b128 v[40:43], v130 offset:4608
	v_pk_fma_f32 v[16:17], v[6:7], v[82:83], v[16:17]
	v_pk_fma_f32 v[18:19], v[14:15], v[82:83], v[18:19]
	ds_read_b128 v[44:47], v130 offset:4624
	v_pk_mul_f32 v[20:21], v[2:3], v[92:93]
	v_add_f32_e32 v24, v16, v17
	ds_read_b128 v[56:59], v130 offset:12800
	v_add_f32_e32 v25, v18, v19
	v_pk_mul_f32 v[22:23], v[10:11], v[92:93]
	ds_read_b128 v[60:63], v130 offset:12816
	v_add_f32_dpp v24, v24, v24 quad_perm:[1,0,3,2] row_mask:0xf bank_mask:0xf bound_ctrl:1
	v_add_f32_dpp v25, v25, v25 quad_perm:[1,0,3,2] row_mask:0xf bank_mask:0xf bound_ctrl:1
	ds_read_b128 v[64:67], v130 offset:16896
	v_pk_fma_f32 v[20:21], v[0:1], v[90:91], v[20:21]
	v_add_f32_dpp v24, v24, v24 quad_perm:[2,3,0,1] row_mask:0xf bank_mask:0xf bound_ctrl:1
	ds_read_b128 v[68:71], v130 offset:16912
	v_add_f32_dpp v25, v25, v25 quad_perm:[2,3,0,1] row_mask:0xf bank_mask:0xf bound_ctrl:1
	v_pk_fma_f32 v[22:23], v[8:9], v[90:91], v[22:23]
	ds_read_b128 v[48:51], v130 offset:8704
	v_add_f32_dpp v24, v24, v24 row_half_mirror row_mask:0xf bank_mask:0xf bound_ctrl:1
	v_add_f32_dpp v25, v25, v25 row_half_mirror row_mask:0xf bank_mask:0xf bound_ctrl:1
	ds_read_b128 v[52:55], v130 offset:8720
	v_pk_fma_f32 v[20:21], v[4:5], v[94:95], v[20:21]
	v_pk_fma_f32 v[22:23], v[12:13], v[94:95], v[22:23]
	v_pk_fma_f32 v[20:21], v[6:7], v[96:97], v[20:21]
	v_pk_fma_f32 v[22:23], v[14:15], v[96:97], v[22:23]
	v_add_f32_e32 v26, v20, v21
	v_add_f32_e32 v27, v22, v23
	v_pk_fma_f32 v[178:179], v[24:25], v[142:143], v[26:27] op_sel_hi:[1,0,1]
	v_pk_mul_f32 v[164:165], v[112:113], v[24:25] op_sel_hi:[1,0]
	v_pk_mul_f32 v[166:167], v[112:113], v[24:25] op_sel:[0,1]
	v_pk_mul_f32 v[168:169], v[114:115], v[24:25] op_sel_hi:[1,0]
	v_pk_mul_f32 v[170:171], v[114:115], v[24:25] op_sel:[0,1]
	v_pk_fma_f32 v[164:165], v[120:121], v[74:75], v[164:165] op_sel_hi:[1,0,1]
	v_pk_fma_f32 v[166:167], v[120:121], v[74:75], v[166:167] op_sel:[0,1,0]
	v_pk_fma_f32 v[168:169], v[122:123], v[74:75], v[168:169] op_sel_hi:[1,0,1]
	v_pk_fma_f32 v[170:171], v[122:123], v[74:75], v[170:171] op_sel:[0,1,0]
	v_pk_fma_f32 v[0:1], v[0:1], v[98:99], v[164:165]
	v_pk_fma_f32 v[8:9], v[8:9], v[98:99], v[166:167]
	v_pk_fma_f32 v[2:3], v[2:3], v[100:101], v[168:169]
	v_pk_fma_f32 v[10:11], v[10:11], v[100:101], v[170:171]
	v_pk_mul_f32 v[164:165], v[116:117], v[24:25] op_sel_hi:[1,0]
	v_pk_mul_f32 v[166:167], v[116:117], v[24:25] op_sel:[0,1]
	v_pk_mul_f32 v[168:169], v[118:119], v[24:25] op_sel_hi:[1,0]
	v_pk_mul_f32 v[170:171], v[118:119], v[24:25] op_sel:[0,1]
	v_pk_fma_f32 v[164:165], v[124:125], v[74:75], v[164:165] op_sel_hi:[1,0,1]
	v_pk_fma_f32 v[166:167], v[124:125], v[74:75], v[166:167] op_sel:[0,1,0]
	v_pk_fma_f32 v[168:169], v[126:127], v[74:75], v[168:169] op_sel_hi:[1,0,1]
	v_pk_fma_f32 v[170:171], v[126:127], v[74:75], v[170:171] op_sel:[0,1,0]
	v_pk_fma_f32 v[4:5], v[4:5], v[102:103], v[164:165]
	v_pk_fma_f32 v[12:13], v[12:13], v[102:103], v[166:167]
	v_pk_fma_f32 v[6:7], v[6:7], v[104:105], v[168:169]
	v_pk_fma_f32 v[14:15], v[14:15], v[104:105], v[170:171]
	v_pk_fma_f32 v[178:179], v[74:75], v[142:143], v[178:179] op_sel:[0,1,0]
	s_waitcnt lgkmcnt(0)
	v_pk_mul_f32 v[16:17], v[2:3], v[34:35]
	v_pk_mul_f32 v[18:19], v[10:11], v[34:35]
	ds_read_b128 v[76:79], v130 offset:768
	v_pk_fma_f32 v[16:17], v[0:1], v[32:33], v[16:17]
	v_pk_fma_f32 v[18:19], v[8:9], v[32:33], v[18:19]
	ds_read_b128 v[80:83], v130 offset:784
	v_pk_fma_f32 v[16:17], v[4:5], v[36:37], v[16:17]
	v_pk_fma_f32 v[18:19], v[12:13], v[36:37], v[18:19]
	ds_read_b128 v[90:93], v130 offset:4864
	v_pk_fma_f32 v[16:17], v[6:7], v[38:39], v[16:17]
	v_pk_fma_f32 v[18:19], v[14:15], v[38:39], v[18:19]
	ds_read_b128 v[94:97], v130 offset:4880
	v_pk_mul_f32 v[20:21], v[2:3], v[42:43]
	v_add_f32_e32 v24, v16, v17
	ds_read_b128 v[112:115], v130 offset:13056
	v_add_f32_e32 v25, v18, v19
	v_pk_mul_f32 v[22:23], v[10:11], v[42:43]
	ds_read_b128 v[116:119], v130 offset:13072
	v_add_f32_dpp v24, v24, v24 quad_perm:[1,0,3,2] row_mask:0xf bank_mask:0xf bound_ctrl:1
	v_add_f32_dpp v25, v25, v25 quad_perm:[1,0,3,2] row_mask:0xf bank_mask:0xf bound_ctrl:1
	ds_read_b128 v[120:123], v130 offset:17152
	v_pk_fma_f32 v[20:21], v[0:1], v[40:41], v[20:21]
	v_add_f32_dpp v24, v24, v24 quad_perm:[2,3,0,1] row_mask:0xf bank_mask:0xf bound_ctrl:1
	ds_read_b128 v[124:127], v130 offset:17168
	v_add_f32_dpp v25, v25, v25 quad_perm:[2,3,0,1] row_mask:0xf bank_mask:0xf bound_ctrl:1
	v_pk_fma_f32 v[22:23], v[8:9], v[40:41], v[22:23]
	ds_read_b128 v[98:101], v130 offset:8960
	v_add_f32_dpp v24, v24, v24 row_half_mirror row_mask:0xf bank_mask:0xf bound_ctrl:1
	v_add_f32_dpp v25, v25, v25 row_half_mirror row_mask:0xf bank_mask:0xf bound_ctrl:1
	ds_read_b128 v[102:105], v130 offset:8976
	v_pk_fma_f32 v[20:21], v[4:5], v[44:45], v[20:21]
	v_pk_fma_f32 v[22:23], v[12:13], v[44:45], v[22:23]
	ds_read2_b64 v[72:75], v131 offset0:128 offset1:160
	v_pk_fma_f32 v[20:21], v[6:7], v[46:47], v[20:21]
	v_pk_fma_f32 v[22:23], v[14:15], v[46:47], v[22:23]
	ds_read2_b64 v[140:143], v85 offset0:8 offset1:10
	v_add_f32_e32 v26, v20, v21
	v_add_f32_e32 v27, v22, v23
	v_pk_fma_f32 v[180:181], v[24:25], v[144:145], v[26:27] op_sel_hi:[1,0,1]
	v_pk_mul_f32 v[164:165], v[56:57], v[24:25] op_sel_hi:[1,0]
	v_pk_mul_f32 v[166:167], v[56:57], v[24:25] op_sel:[0,1]
	v_pk_mul_f32 v[168:169], v[58:59], v[24:25] op_sel_hi:[1,0]
	v_pk_mul_f32 v[170:171], v[58:59], v[24:25] op_sel:[0,1]
	v_pk_fma_f32 v[164:165], v[64:65], v[106:107], v[164:165] op_sel_hi:[1,0,1]
	v_pk_fma_f32 v[166:167], v[64:65], v[106:107], v[166:167] op_sel:[0,1,0]
	v_pk_fma_f32 v[168:169], v[66:67], v[106:107], v[168:169] op_sel_hi:[1,0,1]
	v_pk_fma_f32 v[170:171], v[66:67], v[106:107], v[170:171] op_sel:[0,1,0]
	v_pk_fma_f32 v[0:1], v[0:1], v[48:49], v[164:165]
	v_pk_fma_f32 v[8:9], v[8:9], v[48:49], v[166:167]
	v_pk_fma_f32 v[2:3], v[2:3], v[50:51], v[168:169]
	v_pk_fma_f32 v[10:11], v[10:11], v[50:51], v[170:171]
	v_pk_mul_f32 v[164:165], v[60:61], v[24:25] op_sel_hi:[1,0]
	v_pk_mul_f32 v[166:167], v[60:61], v[24:25] op_sel:[0,1]
	v_pk_mul_f32 v[168:169], v[62:63], v[24:25] op_sel_hi:[1,0]
	v_pk_mul_f32 v[170:171], v[62:63], v[24:25] op_sel:[0,1]
	v_pk_fma_f32 v[164:165], v[68:69], v[106:107], v[164:165] op_sel_hi:[1,0,1]
	v_pk_fma_f32 v[166:167], v[68:69], v[106:107], v[166:167] op_sel:[0,1,0]
	v_pk_fma_f32 v[168:169], v[70:71], v[106:107], v[168:169] op_sel_hi:[1,0,1]
	v_pk_fma_f32 v[170:171], v[70:71], v[106:107], v[170:171] op_sel:[0,1,0]
	v_pk_fma_f32 v[4:5], v[4:5], v[52:53], v[164:165]
	v_pk_fma_f32 v[12:13], v[12:13], v[52:53], v[166:167]
	v_pk_fma_f32 v[6:7], v[6:7], v[54:55], v[168:169]
	v_pk_fma_f32 v[14:15], v[14:15], v[54:55], v[170:171]
	v_pk_fma_f32 v[180:181], v[106:107], v[144:145], v[180:181] op_sel:[0,1,0]
	s_waitcnt lgkmcnt(0)
	v_pk_mul_f32 v[16:17], v[2:3], v[78:79]
	v_pk_mul_f32 v[18:19], v[10:11], v[78:79]
	ds_read_b128 v[32:35], v130 offset:1024
	v_pk_fma_f32 v[16:17], v[0:1], v[76:77], v[16:17]
	v_pk_fma_f32 v[18:19], v[8:9], v[76:77], v[18:19]
	ds_read_b128 v[36:39], v130 offset:1040
	v_pk_fma_f32 v[16:17], v[4:5], v[80:81], v[16:17]
	v_pk_fma_f32 v[18:19], v[12:13], v[80:81], v[18:19]
	ds_read_b128 v[40:43], v130 offset:5120
	v_pk_fma_f32 v[16:17], v[6:7], v[82:83], v[16:17]
	v_pk_fma_f32 v[18:19], v[14:15], v[82:83], v[18:19]
	ds_read_b128 v[44:47], v130 offset:5136
	v_pk_mul_f32 v[20:21], v[2:3], v[92:93]
	v_add_f32_e32 v24, v16, v17
	ds_read_b128 v[56:59], v130 offset:13312
	v_add_f32_e32 v25, v18, v19
	v_pk_mul_f32 v[22:23], v[10:11], v[92:93]
	ds_read_b128 v[60:63], v130 offset:13328
	v_add_f32_dpp v24, v24, v24 quad_perm:[1,0,3,2] row_mask:0xf bank_mask:0xf bound_ctrl:1
	v_add_f32_dpp v25, v25, v25 quad_perm:[1,0,3,2] row_mask:0xf bank_mask:0xf bound_ctrl:1
	ds_read_b128 v[64:67], v130 offset:17408
	v_pk_fma_f32 v[20:21], v[0:1], v[90:91], v[20:21]
	v_add_f32_dpp v24, v24, v24 quad_perm:[2,3,0,1] row_mask:0xf bank_mask:0xf bound_ctrl:1
	ds_read_b128 v[68:71], v130 offset:17424
	v_add_f32_dpp v25, v25, v25 quad_perm:[2,3,0,1] row_mask:0xf bank_mask:0xf bound_ctrl:1
	v_pk_fma_f32 v[22:23], v[8:9], v[90:91], v[22:23]
	ds_read_b128 v[48:51], v130 offset:9216
	v_add_f32_dpp v24, v24, v24 row_half_mirror row_mask:0xf bank_mask:0xf bound_ctrl:1
	v_add_f32_dpp v25, v25, v25 row_half_mirror row_mask:0xf bank_mask:0xf bound_ctrl:1
	ds_read_b128 v[52:55], v130 offset:9232
	v_pk_fma_f32 v[20:21], v[4:5], v[94:95], v[20:21]
	v_pk_fma_f32 v[22:23], v[12:13], v[94:95], v[22:23]
	v_pk_fma_f32 v[20:21], v[6:7], v[96:97], v[20:21]
	v_pk_fma_f32 v[22:23], v[14:15], v[96:97], v[22:23]
	v_add_f32_e32 v26, v20, v21
	v_add_f32_e32 v27, v22, v23
	v_pk_fma_f32 v[182:183], v[24:25], v[146:147], v[26:27] op_sel_hi:[1,0,1]
	v_pk_mul_f32 v[164:165], v[112:113], v[24:25] op_sel_hi:[1,0]
	v_pk_mul_f32 v[166:167], v[112:113], v[24:25] op_sel:[0,1]
	v_pk_mul_f32 v[168:169], v[114:115], v[24:25] op_sel_hi:[1,0]
	v_pk_mul_f32 v[170:171], v[114:115], v[24:25] op_sel:[0,1]
	v_pk_fma_f32 v[164:165], v[120:121], v[108:109], v[164:165] op_sel_hi:[1,0,1]
	v_pk_fma_f32 v[166:167], v[120:121], v[108:109], v[166:167] op_sel:[0,1,0]
	v_pk_fma_f32 v[168:169], v[122:123], v[108:109], v[168:169] op_sel_hi:[1,0,1]
	v_pk_fma_f32 v[170:171], v[122:123], v[108:109], v[170:171] op_sel:[0,1,0]
	v_pk_fma_f32 v[0:1], v[0:1], v[98:99], v[164:165]
	v_pk_fma_f32 v[8:9], v[8:9], v[98:99], v[166:167]
	v_pk_fma_f32 v[2:3], v[2:3], v[100:101], v[168:169]
	v_pk_fma_f32 v[10:11], v[10:11], v[100:101], v[170:171]
	v_pk_mul_f32 v[164:165], v[116:117], v[24:25] op_sel_hi:[1,0]
	v_pk_mul_f32 v[166:167], v[116:117], v[24:25] op_sel:[0,1]
	v_pk_mul_f32 v[168:169], v[118:119], v[24:25] op_sel_hi:[1,0]
	v_pk_mul_f32 v[170:171], v[118:119], v[24:25] op_sel:[0,1]
	v_pk_fma_f32 v[164:165], v[124:125], v[108:109], v[164:165] op_sel_hi:[1,0,1]
	v_pk_fma_f32 v[166:167], v[124:125], v[108:109], v[166:167] op_sel:[0,1,0]
	v_pk_fma_f32 v[168:169], v[126:127], v[108:109], v[168:169] op_sel_hi:[1,0,1]
	v_pk_fma_f32 v[170:171], v[126:127], v[108:109], v[170:171] op_sel:[0,1,0]
	v_pk_fma_f32 v[4:5], v[4:5], v[102:103], v[164:165]
	v_pk_fma_f32 v[12:13], v[12:13], v[102:103], v[166:167]
	v_pk_fma_f32 v[6:7], v[6:7], v[104:105], v[168:169]
	v_pk_fma_f32 v[14:15], v[14:15], v[104:105], v[170:171]
	v_pk_fma_f32 v[182:183], v[108:109], v[146:147], v[182:183] op_sel:[0,1,0]
	v_add_f32_dpp v176, v176, v176 row_half_mirror row_mask:0xf bank_mask:0x5
	v_add_f32_dpp v176, v180, v180 row_half_mirror row_mask:0xf bank_mask:0xa
	v_add_f32_dpp v177, v177, v177 row_half_mirror row_mask:0xf bank_mask:0x5
	v_add_f32_dpp v177, v181, v181 row_half_mirror row_mask:0xf bank_mask:0xa
	v_add_f32_dpp v178, v178, v178 row_half_mirror row_mask:0xf bank_mask:0x5
	v_add_f32_dpp v178, v182, v182 row_half_mirror row_mask:0xf bank_mask:0xa
	v_add_f32_dpp v179, v179, v179 row_half_mirror row_mask:0xf bank_mask:0x5
	v_add_f32_dpp v179, v183, v183 row_half_mirror row_mask:0xf bank_mask:0xa
	v_cndmask_b32_e64 v16, v178, v176, s[46:47]
	v_cndmask_b32_e64 v17, v176, v178, s[46:47]
	v_cndmask_b32_e64 v18, v179, v177, s[46:47]
	v_cndmask_b32_e64 v19, v177, v179, s[46:47]
	v_add_u32_e32 v130, 0x400, v130
	v_add_f32_dpp v176, v17, v16 quad_perm:[2,3,0,1] row_mask:0xf bank_mask:0xf bound_ctrl:1
	v_add_u32_e32 v131, 0x400, v131
	v_add_f32_dpp v177, v19, v18 quad_perm:[2,3,0,1] row_mask:0xf bank_mask:0xf bound_ctrl:1
	v_add_u32_e32 v85, 64, v85
	v_cndmask_b32_e64 v16, v177, v176, s[48:49]
	v_cndmask_b32_e64 v17, v176, v177, s[48:49]
	s_add_i32 s0, s0, -1
	s_cmp_lg_u32 s0, 0
	v_add_f32_dpp v18, v17, v16 quad_perm:[1,0,3,2] row_mask:0xf bank_mask:0xf bound_ctrl:1
	s_nop 0
	ds_write_b32 v86, v18
	v_add_u32_e32 v86, 0x400, v86
	s_cbranch_scc1 .Lscan_q4
	s_xor_b32 s1, s1, 0x8200
	s_add_i32 s2, s2, -1
	s_waitcnt lgkmcnt(0)
	s_barrier
	s_cmp_lg_u32 s2, 0
	s_cbranch_scc1 .Lscan_chunk
	s_setprio 0
	s_branch .LBB0_627
